# stagger classes by XCD parity (bid bit 0) instead of M-tile parity within each XCD: whole XCDs 1,3,5,7 start the chain ~14 us late
# baseline (speedup 1.0000x reference)
.LBB0_539:
	s_or_b64 exec, exec, s[0:1]
	v_mov_b32_e32 v0, v154
	v_readlane_b32 s6, v253, 0
	s_waitcnt lgkmcnt(0)
	s_barrier
	v_readlane_b32 s8, v253, 0
	s_bitcmp1_b32 s8, 0
	s_cbranch_scc0 .Lstag_skip
	s_sleep 127
	s_sleep 127
	s_sleep 127
	s_sleep 127
